# split-phase waits issue the L1 invalidate before polling
# baseline (speedup 1.0000x reference)
.LBB0_460:
	s_cmp_eq_u32 s100, 1
	s_cbranch_scc0 .Ldf3_wd
	s_mov_b32 s100, 0
	v_cmp_eq_u32_e64 s[98:99], 0, v171
	s_nop 1
	s_and_saveexec_b64 s[98:99], s[98:99]
	s_cbranch_execz .Ldf3_wj
	v_mov_b32_e32 v247, 0x20004
	ds_read_b32 v248, v247
	v_readlane_b32 s96, v246, 1
	v_readlane_b32 s97, v246, 2
	v_mov_b32_e32 v249, 0x3940
	s_mov_b32 s90, 0
	s_waitcnt lgkmcnt(0)
	v_readfirstlane_b32 s101, v248
	s_nop 3
	buffer_inv sc1
.Ldf3_poll:
	global_load_dword v250, v249, s[96:97] sc1
	s_waitcnt vmcnt(0)
	v_readfirstlane_b32 s91, v250
	s_nop 0
	s_cmp_ge_u32 s91, s101
	s_cbranch_scc1 .Ldf3_ok
	s_sleep 1
	s_add_i32 s90, s90, 1
	s_cmp_lt_u32 s90, 0x40000
	s_cbranch_scc1 .Ldf3_poll
.Ldf3_ok:
	s_waitcnt vmcnt(0)
.Ldf3_wj:
	s_or_b64 exec, exec, s[98:99]
	s_barrier

.LBB0_649:
	s_cmp_eq_u32 s100, 1
	s_cbranch_scc0 .Ldf6_wd
	s_mov_b32 s100, 0
	v_cmp_eq_u32_e64 s[98:99], 0, v171
	s_nop 1
	s_and_saveexec_b64 s[98:99], s[98:99]
	s_cbranch_execz .Ldf6_wj
	v_mov_b32_e32 v247, 0x20004
	ds_read_b32 v248, v247
	v_readlane_b32 s96, v246, 1
	v_readlane_b32 s97, v246, 2
	v_mov_b32_e32 v249, 0x39c0
	s_mov_b32 s90, 0
	s_waitcnt lgkmcnt(0)
	v_readfirstlane_b32 s101, v248
	s_nop 3
	buffer_inv sc1
.Ldf6_poll:
	global_load_dword v250, v249, s[96:97] sc1
	s_waitcnt vmcnt(0)
	v_readfirstlane_b32 s91, v250
	s_nop 0
	s_cmp_ge_u32 s91, s101
	s_cbranch_scc1 .Ldf6_ok
	s_sleep 1
	s_add_i32 s90, s90, 1
	s_cmp_lt_u32 s90, 0x40000
	s_cbranch_scc1 .Ldf6_poll
.Ldf6_ok:
	s_waitcnt vmcnt(0)
.Ldf6_wj:
	s_or_b64 exec, exec, s[98:99]
	s_barrier
